# P7 tile epilogue: last full VMEM drain replaced by a counted wait that leaves the 5 trailing y stores in flight
# baseline (speedup 1.0000x reference)
; DI void phase_p7(const Params& P, unsigned char* lds) {
;     ...
;         const int col = n0 + wn * 128 + 4 * r;
;         const size_t crow0 = (size_t)mt * 256 + wm * 64 + 4 * hh;
; #pragma unroll
;         for (int mb = 0; mb < 2; ++mb) {
; #pragma unroll
;           for (int hf = 0; hf < 2; ++hf) {
;             f32x4 yv[16];
; #pragma unroll
;             for (int i = 8 * hf; i < 8 * hf + 8; ++i) yv[i] = *(const f32x4*)(P.out + O_Y + (crow0 + mb * 32 + (i & 3) + 8 * (i >> 2)) * 1024 + col);
; #pragma unroll
;             for (int i = 8 * hf; i < 8 * hf + 8; ++i) {
;                 f32x4 o = yv[i]; o.x += acc[mb][0][i]; o.y += acc[mb][1][i]; o.z += acc[mb][2][i]; o.w += acc[mb][3][i];
;                 __builtin_nontemporal_store(o, (f32x4*)(P.out + O_Y + (crow0 + mb * 32 + (i & 3) + 8 * (i >> 2)) * 1024 + col));
;             }
;           }
;         }
.LBB0_1718:
	v_or_b32_e32 v134, s20, v146
	s_ashr_i32 s19, s18, 31
	v_ashrrev_i32_e32 v135, 31, v134
	v_lshl_add_u64 v[134:135], v[134:135], 2, s[74:75]
	s_lshl_b64 s[18:19], s[18:19], 20
	v_lshl_add_u64 v[134:135], v[134:135], 0, s[18:19]
	v_lshl_add_u64 v[134:135], v[134:135], 0, v[130:131]
	v_add_co_u32_e32 v188, vcc, 0x1000, v134
	v_mov_b32_e32 v204, v114
	s_nop 0
	v_addc_co_u32_e32 v189, vcc, 0, v135, vcc
	v_add_co_u32_e32 v190, vcc, s29, v134
	global_load_dwordx4 v[136:139], v[134:135], off
	global_load_dwordx4 v[140:143], v[188:189], off
	v_addc_co_u32_e32 v191, vcc, 0, v135, vcc
	v_add_co_u32_e32 v192, vcc, 0x3000, v134
	global_load_dwordx4 v[148:151], v[190:191], off
	s_nop 0
	v_addc_co_u32_e32 v193, vcc, 0, v135, vcc
	v_add_co_u32_e32 v194, vcc, s30, v134
	global_load_dwordx4 v[152:155], v[192:193], off
	s_nop 0
	v_addc_co_u32_e32 v195, vcc, 0, v135, vcc
	v_add_co_u32_e32 v196, vcc, 0x9000, v134
	global_load_dwordx4 v[156:159], v[194:195], off
	s_nop 0
	v_addc_co_u32_e32 v197, vcc, 0, v135, vcc
	global_load_dwordx4 v[160:163], v[196:197], off
	v_add_co_u32_e32 v198, vcc, s31, v134
	v_mov_b32_e32 v205, v98
	s_nop 0
	v_addc_co_u32_e32 v199, vcc, 0, v135, vcc
	v_add_co_u32_e32 v200, vcc, 0xb000, v134
	global_load_dwordx4 v[164:167], v[198:199], off
	s_nop 0
	v_addc_co_u32_e32 v201, vcc, 0, v135, vcc
	global_load_dwordx4 v[168:171], v[200:201], off
	v_add_co_u32_e32 v202, vcc, s35, v134
	v_mov_b32_e32 v98, v115
	s_nop 0
	v_addc_co_u32_e32 v203, vcc, 0, v135, vcc
	global_load_dwordx4 v[172:175], v[202:203], off offset:-4096
	global_load_dwordx4 v[176:179], v[202:203], off
	v_add_co_u32_e32 v206, vcc, s36, v134
	v_mov_b32_e32 v210, v116
	s_nop 0
	v_addc_co_u32_e32 v207, vcc, 0, v135, vcc
	global_load_dwordx4 v[180:183], v[206:207], off offset:-4096
	v_mov_b32_e32 v211, v100
	v_mov_b32_e32 v100, v117
	global_load_dwordx4 v[114:117], v[206:207], off
	v_add_co_u32_e32 v214, vcc, s37, v134
	v_mov_b32_e32 v208, v82
	s_nop 0
	v_addc_co_u32_e32 v215, vcc, 0, v135, vcc
	v_mov_b32_e32 v209, v66
	global_load_dwordx4 v[184:187], v[214:215], off offset:-4096
	v_mov_b32_e32 v66, v83
	v_mov_b32_e32 v212, v84
	v_mov_b32_e32 v213, v68
	v_mov_b32_e32 v68, v85
	s_mov_b64 s[24:25], -1
	s_waitcnt vmcnt(0)
	v_pk_add_f32 v[82:83], v[204:205], v[136:137]
	v_pk_add_f32 v[84:85], v[208:209], v[138:139]
	global_store_dwordx4 v[134:135], v[82:85], off nt
	v_pk_add_f32 v[68:69], v[68:69], v[154:155]
	s_nop 0
	v_pk_add_f32 v[82:83], v[98:99], v[140:141]
	v_pk_add_f32 v[84:85], v[66:67], v[142:143]
	v_pk_add_f32 v[66:67], v[100:101], v[152:153]
	global_store_dwordx4 v[188:189], v[82:85], off nt
	global_store_dwordx4 v[192:193], v[66:69], off nt
	global_load_dwordx4 v[98:101], v[214:215], off
	v_pk_add_f32 v[82:83], v[210:211], v[148:149]
	v_pk_add_f32 v[84:85], v[212:213], v[150:151]
	v_mov_b32_e32 v66, v118
	v_mov_b32_e32 v67, v102
	v_mov_b32_e32 v68, v86
	v_mov_b32_e32 v69, v70
	global_store_dwordx4 v[190:191], v[82:85], off nt
	v_pk_add_f32 v[66:67], v[66:67], v[156:157]
	v_pk_add_f32 v[68:69], v[68:69], v[158:159]
	v_mov_b32_e32 v102, v119
	v_mov_b32_e32 v70, v87
	v_add_co_u32_e32 v82, vcc, s38, v134
	global_store_dwordx4 v[194:195], v[66:69], off nt
	s_nop 0
	v_addc_co_u32_e32 v83, vcc, 0, v135, vcc
	v_pk_add_f32 v[66:67], v[102:103], v[160:161]
	v_pk_add_f32 v[68:69], v[70:71], v[162:163]
	global_store_dwordx4 v[196:197], v[66:69], off nt
	global_load_dwordx4 v[66:69], v[82:83], off offset:-4096
	v_mov_b32_e32 v70, v120
	v_mov_b32_e32 v71, v104
	v_pk_add_f32 v[84:85], v[70:71], v[164:165]
	v_mov_b32_e32 v70, v88
	v_mov_b32_e32 v71, v72
	v_mov_b32_e32 v104, v121
	v_mov_b32_e32 v72, v89
	v_pk_add_f32 v[86:87], v[70:71], v[166:167]
	v_pk_add_f32 v[70:71], v[104:105], v[168:169]
	v_pk_add_f32 v[72:73], v[72:73], v[170:171]
	global_store_dwordx4 v[198:199], v[84:87], off nt
	global_store_dwordx4 v[200:201], v[70:73], off nt
	global_load_dwordx4 v[70:73], v[82:83], off
	v_mov_b32_e32 v84, v122
	v_mov_b32_e32 v85, v106
	v_mov_b32_e32 v86, v90
	v_mov_b32_e32 v87, v74
	v_add_co_u32_e32 v136, vcc, s39, v134
	v_pk_add_f32 v[84:85], v[84:85], v[172:173]
	v_pk_add_f32 v[86:87], v[86:87], v[174:175]
	v_addc_co_u32_e32 v137, vcc, 0, v135, vcc
	global_store_dwordx4 v[202:203], v[84:87], off offset:-4096 nt
	global_load_dwordx4 v[84:87], v[136:137], off offset:-4096
	v_mov_b32_e32 v106, v123
	global_load_dwordx4 v[102:105], v[136:137], off
	v_mov_b32_e32 v74, v91
	v_pk_add_f32 v[88:89], v[106:107], v[176:177]
	v_pk_add_f32 v[90:91], v[74:75], v[178:179]
	v_mov_b32_e32 v74, v124
	v_mov_b32_e32 v75, v108
	global_store_dwordx4 v[202:203], v[88:91], off nt
	v_add_co_u32_e32 v138, vcc, s40, v134
	s_nop 0
	v_pk_add_f32 v[88:89], v[74:75], v[180:181]
	v_mov_b32_e32 v74, v92
	v_mov_b32_e32 v75, v76
	v_pk_add_f32 v[90:91], v[74:75], v[182:183]
	v_mov_b32_e32 v108, v125
	v_addc_co_u32_e32 v139, vcc, 0, v135, vcc
	v_mov_b32_e32 v76, v93
	global_store_dwordx4 v[206:207], v[88:91], off offset:-4096 nt
	global_load_dwordx4 v[88:91], v[138:139], off offset:-4096
	v_pk_add_f32 v[74:75], v[108:109], v[114:115]
	v_pk_add_f32 v[76:77], v[76:77], v[116:117]
	global_store_dwordx4 v[206:207], v[74:77], off nt
	v_mov_b32_e32 v92, v126
	global_load_dwordx4 v[74:77], v[138:139], off
	v_mov_b32_e32 v93, v110
	v_add_co_u32_e32 v140, vcc, s41, v134
	v_pk_add_f32 v[114:115], v[92:93], v[184:185]
	s_nop 0
	v_addc_co_u32_e32 v141, vcc, 0, v135, vcc
	v_mov_b32_e32 v92, v94
	v_mov_b32_e32 v93, v78
	global_load_dwordx4 v[106:109], v[140:141], off offset:-4096
	v_pk_add_f32 v[116:117], v[92:93], v[186:187]
	global_store_dwordx4 v[214:215], v[114:117], off offset:-4096 nt
	global_load_dwordx4 v[114:117], v[140:141], off
	v_add_co_u32_e32 v126, vcc, s42, v134
	v_mov_b32_e32 v110, v127
	s_nop 0
	v_addc_co_u32_e32 v127, vcc, 0, v135, vcc
	v_mov_b32_e32 v78, v95
	global_load_dwordx4 v[118:121], v[126:127], off offset:-4096
	s_waitcnt vmcnt(0)
; DI void phase_p7(const Params& P, unsigned char* lds) {
;     ...
;         const int col = n0 + wn * 128 + 4 * r;
;         const size_t crow0 = (size_t)mt * 256 + wm * 64 + 4 * hh;
; #pragma unroll
;         for (int mb = 0; mb < 2; ++mb) {
; #pragma unroll
;           for (int hf = 0; hf < 2; ++hf) {
;             f32x4 yv[16];
; #pragma unroll
;             for (int i = 8 * hf; i < 8 * hf + 8; ++i) yv[i] = *(const f32x4*)(P.out + O_Y + (crow0 + mb * 32 + (i & 3) + 8 * (i >> 2)) * 1024 + col);
; #pragma unroll
;             for (int i = 8 * hf; i < 8 * hf + 8; ++i) {
;                 f32x4 o = yv[i]; o.x += acc[mb][0][i]; o.y += acc[mb][1][i]; o.z += acc[mb][2][i]; o.w += acc[mb][3][i];
;                 __builtin_nontemporal_store(o, (f32x4*)(P.out + O_Y + (crow0 + mb * 32 + (i & 3) + 8 * (i >> 2)) * 1024 + col));
;             }
;           }
;         }
	v_pk_add_f32 v[92:93], v[110:111], v[98:99]
	v_pk_add_f32 v[94:95], v[78:79], v[100:101]
	global_store_dwordx4 v[214:215], v[92:95], off nt
	v_mov_b32_e32 v78, v128
	global_load_dwordx4 v[92:95], v[126:127], off
	v_mov_b32_e32 v79, v112
	v_add_co_u32_e32 v142, vcc, s43, v134
	v_mov_b32_e32 v112, v129
	s_nop 0
	v_addc_co_u32_e32 v143, vcc, 0, v135, vcc
	v_pk_add_f32 v[66:67], v[78:79], v[66:67]
	v_mov_b32_e32 v78, v96
	v_mov_b32_e32 v79, v80
	global_load_dwordx4 v[98:101], v[142:143], off offset:-4096
	v_pk_add_f32 v[68:69], v[78:79], v[68:69]
	global_store_dwordx4 v[82:83], v[66:69], off offset:-4096 nt
	global_load_dwordx4 v[66:69], v[142:143], off
	v_add_co_u32_e32 v128, vcc, s44, v134
	v_mov_b32_e32 v80, v97
	s_nop 0
	v_addc_co_u32_e32 v129, vcc, 0, v135, vcc
	global_load_dwordx4 v[122:125], v[128:129], off offset:-4096
	v_pk_add_f32 v[70:71], v[112:113], v[70:71]
	v_pk_add_f32 v[72:73], v[80:81], v[72:73]
	global_store_dwordx4 v[82:83], v[70:73], off nt
	v_mov_b32_e32 v82, v50
	global_load_dwordx4 v[70:73], v[128:129], off
	v_mov_b32_e32 v83, v34
	v_add_co_u32_e32 v96, vcc, s45, v134
	v_mov_b32_e32 v34, v51
	s_nop 0
	v_addc_co_u32_e32 v97, vcc, 0, v135, vcc
	v_pk_add_f32 v[82:83], v[82:83], v[84:85]
	v_mov_b32_e32 v84, v18
	v_mov_b32_e32 v85, v2
	global_load_dwordx4 v[78:81], v[96:97], off offset:-4096
	v_pk_add_f32 v[84:85], v[84:85], v[86:87]
	global_store_dwordx4 v[136:137], v[82:85], off offset:-4096 nt
	global_load_dwordx4 v[82:85], v[96:97], off
	v_add_co_u32_e32 v50, vcc, s46, v134
	v_mov_b32_e32 v2, v19
	s_nop 0
	v_addc_co_u32_e32 v51, vcc, 0, v135, vcc
	global_load_dwordx4 v[110:113], v[50:51], off offset:-4096
	v_pk_add_f32 v[102:103], v[34:35], v[102:103]
	v_pk_add_f32 v[104:105], v[2:3], v[104:105]
	global_store_dwordx4 v[136:137], v[102:105], off nt
	global_load_dwordx4 v[102:105], v[50:51], off
	v_mov_b32_e32 v2, v52
	v_mov_b32_e32 v3, v36
	v_mov_b32_e32 v36, v53
	v_pk_add_f32 v[86:87], v[2:3], v[88:89]
	v_mov_b32_e32 v2, v20
	v_mov_b32_e32 v3, v4
	v_mov_b32_e32 v4, v21
	v_pk_add_f32 v[88:89], v[2:3], v[90:91]
	v_pk_add_f32 v[2:3], v[36:37], v[74:75]
	v_pk_add_f32 v[4:5], v[4:5], v[76:77]
	global_store_dwordx4 v[138:139], v[2:5], off nt
	s_and_b64 vcc, exec, s[22:23]
	global_store_dwordx4 v[138:139], v[86:89], off offset:-4096 nt
	v_mov_b32_e32 v2, v54
	v_mov_b32_e32 v3, v38
	v_mov_b32_e32 v4, v22
	v_mov_b32_e32 v5, v6
	v_pk_add_f32 v[2:3], v[2:3], v[106:107]
	v_pk_add_f32 v[4:5], v[4:5], v[108:109]
	v_mov_b32_e32 v38, v55
	v_mov_b32_e32 v6, v23
	global_store_dwordx4 v[140:141], v[2:5], off offset:-4096 nt
	s_nop 1
	v_pk_add_f32 v[2:3], v[38:39], v[114:115]
	v_pk_add_f32 v[4:5], v[6:7], v[116:117]
	global_store_dwordx4 v[140:141], v[2:5], off nt
	s_nop 1
	v_mov_b32_e32 v2, v56
	v_mov_b32_e32 v3, v40
	v_mov_b32_e32 v4, v24
	v_mov_b32_e32 v5, v8
	v_pk_add_f32 v[2:3], v[2:3], v[118:119]
	v_pk_add_f32 v[4:5], v[4:5], v[120:121]
	v_mov_b32_e32 v40, v57
	v_mov_b32_e32 v8, v25
	global_store_dwordx4 v[126:127], v[2:5], off offset:-4096 nt
	s_waitcnt vmcnt(5)
	s_nop 0
	v_pk_add_f32 v[2:3], v[40:41], v[92:93]
	v_pk_add_f32 v[4:5], v[8:9], v[94:95]
	global_store_dwordx4 v[126:127], v[2:5], off nt
	s_nop 1
	v_mov_b32_e32 v2, v58
	v_mov_b32_e32 v3, v42
	v_mov_b32_e32 v4, v26
	v_mov_b32_e32 v5, v10
	v_pk_add_f32 v[2:3], v[2:3], v[98:99]
	v_pk_add_f32 v[4:5], v[4:5], v[100:101]
	v_mov_b32_e32 v42, v59
	v_mov_b32_e32 v10, v27
	global_store_dwordx4 v[142:143], v[2:5], off offset:-4096 nt
	s_nop 1
	v_pk_add_f32 v[2:3], v[42:43], v[66:67]
	v_pk_add_f32 v[4:5], v[10:11], v[68:69]
	global_store_dwordx4 v[142:143], v[2:5], off nt
	s_nop 1
	v_mov_b32_e32 v2, v60
	v_mov_b32_e32 v3, v44
	v_mov_b32_e32 v4, v28
	v_mov_b32_e32 v5, v12
	v_pk_add_f32 v[2:3], v[2:3], v[122:123]
	v_pk_add_f32 v[4:5], v[4:5], v[124:125]
	v_mov_b32_e32 v44, v61
	v_mov_b32_e32 v12, v29
	global_store_dwordx4 v[128:129], v[2:5], off offset:-4096 nt
	s_nop 1
	v_pk_add_f32 v[2:3], v[44:45], v[70:71]
	v_pk_add_f32 v[4:5], v[12:13], v[72:73]
	global_store_dwordx4 v[128:129], v[2:5], off nt
	s_nop 1
	v_mov_b32_e32 v2, v62
	v_mov_b32_e32 v3, v46
	v_mov_b32_e32 v4, v30
	v_mov_b32_e32 v5, v14
	v_pk_add_f32 v[2:3], v[2:3], v[78:79]
	v_pk_add_f32 v[4:5], v[4:5], v[80:81]
	v_mov_b32_e32 v46, v63
	v_mov_b32_e32 v14, v31
	global_store_dwordx4 v[96:97], v[2:5], off offset:-4096 nt
	s_nop 1
	v_pk_add_f32 v[2:3], v[46:47], v[82:83]
	v_pk_add_f32 v[4:5], v[14:15], v[84:85]
	global_store_dwordx4 v[96:97], v[2:5], off nt
	s_nop 1
	v_mov_b32_e32 v2, v64
	v_mov_b32_e32 v3, v48
	v_mov_b32_e32 v4, v32
	v_mov_b32_e32 v5, v16
	v_pk_add_f32 v[2:3], v[2:3], v[110:111]
	v_pk_add_f32 v[4:5], v[4:5], v[112:113]
	v_mov_b32_e32 v48, v65
	v_mov_b32_e32 v16, v33
	global_store_dwordx4 v[50:51], v[2:5], off offset:-4096 nt
	s_nop 1
	v_pk_add_f32 v[2:3], v[48:49], v[102:103]
	v_pk_add_f32 v[4:5], v[16:17], v[104:105]
	global_store_dwordx4 v[50:51], v[2:5], off nt
	s_cbranch_vccnz .LBB0_1727
